# banded mode-2 item remap, XCD-aware: workgroup = 4 q-heads of a kv head x 2 query blocks, an XCD's workgroups cover 8 adjacent query pairs (K/V tile reuse in L1 and L2)
# baseline (speedup 1.0000x reference)
.LBB0_901:
	s_bfe_u32 s4, s47, 0x30003
	s_lshl_b32 s4, s4, 3
	s_bfe_u32 s6, s47, 0x30006
	s_or_b32 s4, s4, s6
	s_lshl_b32 s4, s4, 6
	s_bfe_u32 s50, s47, 0x10002
	s_lshl_b32 s50, s50, 5
	s_or_b32 s50, s50, s4
	s_add_i32 s5, s50, 0x9f
	s_add_i32 s4, s50, 0xffffff80
	s_lshr_b32 s5, s5, 6
	s_bfe_u32 s48, s47, 0x20009
	s_lshl_b32 s48, s48, 2
	s_and_b32 s6, s47, 3
	s_or_b32 s48, s48, s6
	s_ashr_i32 s49, s47, 11
	s_ashr_i32 s4, s4, 6
	s_add_i32 s5, s5, 1
	s_cmpk_lt_u32 s50, 0xf61
	s_cselect_b32 s51, s5, 64
	v_mov_b32_e32 v49, 0
	s_cmp_ge_i32 s4, s51
	v_mov_b32_e32 v48, 0
	v_mov_b32_e32 v47, 0
	v_mov_b32_e32 v46, 0
	v_mov_b32_e32 v45, 0
	v_mov_b32_e32 v44, 0
	v_mov_b32_e32 v43, 0
	v_mov_b32_e32 v42, 0
	v_mov_b32_e32 v41, 0
	v_mov_b32_e32 v40, 0
	v_mov_b32_e32 v39, 0
	v_mov_b32_e32 v38, 0
	v_mov_b32_e32 v37, 0
	v_mov_b32_e32 v36, 0
	v_mov_b32_e32 v35, 0
	v_mov_b32_e32 v34, 0
	v_mov_b32_e32 v65, 0
	v_mov_b32_e32 v64, 0
	v_mov_b32_e32 v63, 0
	v_mov_b32_e32 v62, 0
	v_mov_b32_e32 v61, 0
	v_mov_b32_e32 v60, 0
	v_mov_b32_e32 v59, 0
	v_mov_b32_e32 v58, 0
	v_mov_b32_e32 v57, 0
	v_mov_b32_e32 v56, 0
	v_mov_b32_e32 v55, 0
	v_mov_b32_e32 v54, 0
	v_mov_b32_e32 v53, 0
	v_mov_b32_e32 v52, 0
	v_mov_b32_e32 v51, 0
	v_mov_b32_e32 v50, 0
	v_mov_b32_e32 v214, v179
	s_cbranch_scc1 .LBB0_900
	s_mov_b32 s5, s50
	v_subrev_u32_e32 v212, s5, v211
	s_lshl_b32 s5, s49, 4
	s_or_b32 s6, s5, s48
	s_ashr_i32 s7, s6, 31
	s_lshl_b64 s[6:7], s[6:7], 12
	s_or_b32 s5, s6, s50
	v_mov_b32_e32 v1, s7
	v_or_b32_e32 v0, s5, v178
	s_lshr_b32 s5, s48, 2
	s_lshl_b32 s6, s49, 2
	v_lshlrev_b64 v[0:1], 7, v[0:1]
	s_or_b32 s6, s5, s6
	s_not_b32 s5, s48
	v_lshl_add_u64 v[0:1], v[180:181], 0, v[0:1]
	s_lshl_b32 s5, s5, 3
	global_load_dwordx4 v[98:101], v[0:1], off
	global_load_dwordx4 v[102:105], v[0:1], off offset:32
	global_load_dwordx4 v[106:109], v[0:1], off offset:64
	global_load_dwordx4 v[110:113], v[0:1], off offset:96
	v_cvt_f32_i32_e32 v0, s5
	s_ashr_i32 s7, s6, 31
	s_lshl_b64 s[6:7], s[6:7], 19
	v_lshl_add_u64 v[204:205], v[182:183], 0, s[6:7]
	v_mul_f32_e32 v1, 0x3d800000, v0
	v_cmp_gt_f32_e32 vcc, s8, v1
	v_lshl_add_u64 v[206:207], v[184:185], 0, s[6:7]
	s_and_b64 s[6:7], vcc, exec
	v_cndmask_b32_e32 v1, 0, v241, vcc
	v_fmac_f32_e32 v1, 0x3d800000, v0
	v_exp_f32_e32 v0, v1
	s_cselect_b32 s5, 0xffffffc0, 0
	s_mov_b64 s[6:7], s[58:59]
	s_mov_b32 s8, s65
	v_ldexp_f32 v0, v0, s5
	s_lshl_b32 s5, s48, 2
	v_mul_f32_e32 v4, 0x3fb8aa3b, v0
	v_mov_b32_e32 v0, s5
	s_mov_b32 s5, s64
	s_mov_b32 s9, s57
	v_readlane_b32 s52, v253, 2
	v_readlane_b32 s56, v253, 6
	v_readlane_b32 s57, v253, 7
	s_max_i32 s52, s4, 0
	s_lshl_b32 s16, s52, 13
	v_mov_b32_e32 v46, v33
	v_mov_b32_e32 v47, v33
	v_mov_b32_e32 v32, v33
	global_load_dword v0, v0, s[56:57]
	v_lshl_add_u64 v[6:7], v[204:205], 0, s[16:17]
	v_add_co_u32_e32 v8, vcc, s79, v6
	v_mov_b32_e32 v34, v33
	v_mov_b32_e32 v35, v33
	v_addc_co_u32_e32 v9, vcc, 0, v7, vcc
	global_load_dwordx4 v[114:117], v[8:9], off offset:3072
	global_load_dwordx4 v[118:121], v[8:9], off offset:2048
	global_load_dwordx4 v[122:125], v[8:9], off offset:1024
	global_load_dwordx4 v[126:129], v[8:9], off
	global_load_dwordx4 v[130:133], v[6:7], off offset:3072
	global_load_dwordx4 v[134:137], v[6:7], off offset:2048
	global_load_dwordx4 v[138:141], v[6:7], off offset:1024
	global_load_dwordx4 v[142:145], v[6:7], off
	v_lshl_add_u64 v[10:11], v[206:207], 0, s[16:17]
	global_load_dwordx4 v[174:177], v[10:11], off offset:-4096
	global_load_dwordx4 v[170:173], v[10:11], off offset:-3072
	global_load_dwordx4 v[166:169], v[10:11], off offset:-2048
	global_load_dwordx4 v[162:165], v[10:11], off offset:-1024
	global_load_dwordx4 v[158:161], v[10:11], off
	global_load_dwordx4 v[154:157], v[10:11], off offset:1024
	global_load_dwordx4 v[150:153], v[10:11], off offset:2048
	global_load_dwordx4 v[146:149], v[10:11], off offset:3072
	v_mov_b32_e32 v36, v33
	v_mov_b32_e32 v37, v33
	v_mov_b32_e32 v38, v33
	v_mov_b32_e32 v39, v33
	v_mov_b32_e32 v40, v33
	v_mov_b32_e32 v41, v33
	v_mov_b32_e32 v42, v33
	v_mov_b32_e32 v43, v33
	v_mov_b32_e32 v44, v33
	v_mov_b32_e32 v45, v33
	v_mov_b64_e32 v[64:65], v[46:47]
	v_readlane_b32 s53, v253, 3
	v_readlane_b32 s54, v253, 4
	v_readlane_b32 s55, v253, 5
	v_readlane_b32 s58, v253, 8
	v_readlane_b32 s59, v253, 9
	v_readlane_b32 s60, v253, 10
	v_readlane_b32 s61, v253, 11
	v_readlane_b32 s62, v253, 12
	v_readlane_b32 s63, v253, 13
	v_readlane_b32 s64, v253, 14
	v_readlane_b32 s65, v253, 15
	v_readlane_b32 s66, v253, 16
	v_readlane_b32 s67, v253, 17
	v_readfirstlane_b32 s38, v4
	v_mov_b64_e32 v[62:63], v[44:45]
	v_mov_b64_e32 v[60:61], v[42:43]
	v_mov_b64_e32 v[58:59], v[40:41]
	v_mov_b64_e32 v[56:57], v[38:39]
	v_mov_b64_e32 v[54:55], v[36:37]
	v_mov_b64_e32 v[52:53], v[34:35]
	v_mov_b64_e32 v[50:51], v[32:33]
	v_mov_b64_e32 v[48:49], v[46:47]
	s_mov_b32 s65, s8
	s_mov_b32 s64, s5
	s_mov_b64 s[58:59], s[6:7]
	s_mov_b32 s57, s9
	s_add_i32 s53, s50, 0x42
	s_add_i32 s54, s50, 0xffffff9e
	s_mov_b32 s39, s38
	s_mov_b32 s55, s38
	s_mov_b32 s60, s38
	s_mov_b32 s61, s38
	s_mov_b32 s62, s38
	s_mov_b32 s63, s38
	s_mov_b32 s66, s38
	s_mov_b32 s67, s38
	s_mov_b32 s69, s38
	s_mov_b32 s70, s38
	s_mov_b32 s71, s38
	s_mov_b32 s80, s38
	s_mov_b32 s81, s38
	s_mov_b32 s82, s38
	s_mov_b32 s83, s38
	s_mov_b32 s84, s38
	s_mov_b32 s85, s38
	s_mov_b32 s86, s38
	s_mov_b32 s87, s38
	s_mov_b32 s88, s38
	s_mov_b32 s89, s38
	s_mov_b32 s93, s38
	s_mov_b32 s94, s38
	s_mov_b32 s95, s38
	s_mov_b32 s96, s38
	s_mov_b32 s97, s38
	s_mov_b32 s4, s38
	s_mov_b32 s5, s38
	s_mov_b32 s6, s38
	s_mov_b32 s7, s38
	s_mov_b32 s8, s38
	s_lshl_b32 s9, s52, 6
	s_mov_b64 s[40:41], s[16:17]
	v_mov_b64_e32 v[46:47], v[44:45]
	v_mov_b64_e32 v[44:45], v[42:43]
	v_mov_b64_e32 v[42:43], v[40:41]
	v_mov_b64_e32 v[40:41], v[38:39]
	v_mov_b64_e32 v[38:39], v[36:37]
	s_waitcnt vmcnt(16)
	v_mul_f32_e32 v213, 0x3fb8aa3b, v0
	v_mov_b64_e32 v[36:37], v[34:35]
	v_mov_b64_e32 v[34:35], v[32:33]
	v_mov_b32_e32 v214, v179
	s_branch .LBB0_904
